# spin cap raised (1M polls); same 7 team-sync sites
# baseline (speedup 1.0000x reference)
FUSE3_SPIN:
	global_load_dword v4, v2, s[20:21] sc1
	s_waitcnt vmcnt(0)
	v_readfirstlane_b32 s69, v4
	s_cmp_ge_u32 s69, 8
	s_cbranch_scc1 FUSE3_GOT
	s_add_i32 s74, s74, 1
	s_cmp_gt_u32 s74, 0x100000
	s_cbranch_scc1 FUSE3_GOT
	s_sleep 1
	s_branch FUSE3_SPIN

FUSE5_SPIN:
	global_load_dword v4, v2, s[20:21] sc1
	s_waitcnt vmcnt(0)
	v_readfirstlane_b32 s69, v4
	s_cmp_ge_u32 s69, 16
	s_cbranch_scc1 FUSE5_GOT
	s_add_i32 s74, s74, 1
	s_cmp_gt_u32 s74, 0x100000
	s_cbranch_scc1 FUSE5_GOT
	s_sleep 1
	s_branch FUSE5_SPIN

FUSE11_SPIN:
	global_load_dword v4, v2, s[20:21] sc1
	s_waitcnt vmcnt(0)
	v_readfirstlane_b32 s69, v4
	s_cmp_ge_u32 s69, 24
	s_cbranch_scc1 FUSE11_GOT
	s_add_i32 s74, s74, 1
	s_cmp_gt_u32 s74, 0x100000
	s_cbranch_scc1 FUSE11_GOT
	s_sleep 1
	s_branch FUSE11_SPIN

FUSE15_SPIN:
	global_load_dword v4, v2, s[20:21] sc1
	s_waitcnt vmcnt(0)
	v_readfirstlane_b32 s69, v4
	s_cmp_ge_u32 s69, 32
	s_cbranch_scc1 FUSE15_GOT
	s_add_i32 s74, s74, 1
	s_cmp_gt_u32 s74, 0x100000
	s_cbranch_scc1 FUSE15_GOT
	s_sleep 1
	s_branch FUSE15_SPIN

FUSE16_SPIN:
	global_load_dword v4, v2, s[20:21] sc1
	s_waitcnt vmcnt(0)
	v_readfirstlane_b32 s69, v4
	s_cmp_ge_u32 s69, 40
	s_cbranch_scc1 FUSE16_GOT
	s_add_i32 s74, s74, 1
	s_cmp_gt_u32 s74, 0x100000
	s_cbranch_scc1 FUSE16_GOT
	s_sleep 1
	s_branch FUSE16_SPIN

FUSE18_SPIN:
	global_load_dword v4, v2, s[20:21] sc1
	s_waitcnt vmcnt(0)
	v_readfirstlane_b32 s69, v4
	s_cmp_ge_u32 s69, 48
	s_cbranch_scc1 FUSE18_GOT
	s_add_i32 s74, s74, 1
	s_cmp_gt_u32 s74, 0x100000
	s_cbranch_scc1 FUSE18_GOT
	s_sleep 1
	s_branch FUSE18_SPIN

FUSE20_SPIN:
	global_load_dword v4, v2, s[20:21] sc1
	s_waitcnt vmcnt(0)
	v_readfirstlane_b32 s69, v4
	s_cmp_ge_u32 s69, 56
	s_cbranch_scc1 FUSE20_GOT
	s_add_i32 s74, s74, 1
	s_cmp_gt_u32 s74, 0x100000
	s_cbranch_scc1 FUSE20_GOT
	s_sleep 1
	s_branch FUSE20_SPIN
